# norm row loop: all 4 rows loads in flight before the single wait (removed three mid-batch vmcnt(0)), on top of DPP reductions
# baseline (speedup 1.0000x reference)
.LBB0_722:
	s_lshl_b32 s3, s35, 3
	v_readlane_b32 s8, v251, 59
	s_add_i32 s10, s8, s3
	s_cmpk_gt_i32 s10, 0x41ff
	s_cbranch_scc1 .LBB0_780
	v_lshlrev_b32_e32 v208, 4, v235
	s_waitcnt vmcnt(0) lgkmcnt(0)
	global_load_dwordx4 v[0:3], v208, s[0:1]
	global_load_dwordx4 v[4:7], v208, s[0:1] offset:1024
	global_load_dwordx4 v[8:11], v208, s[0:1] offset:2048
	global_load_dwordx4 v[12:15], v208, s[0:1] offset:3072
	s_lshl_b32 s30, s41, 3
	s_mul_hi_u32 s0, s14, 0x318000
	s_mul_i32 s14, s14, 0x318000
	v_readlane_b32 s8, v251, 57
	v_readlane_b32 s9, v251, 58
	s_add_u32 s1, s8, s14
	s_addc_u32 s0, s9, s0
	s_lshl_b32 s2, s2, 2
	s_add_u32 s1, s1, s2
	s_addc_u32 s0, s0, 0
	s_add_u32 s31, s1, 0x200000
	v_lshlrev_b32_e32 v16, 3, v235
	v_mov_b32_e32 v17, v209
	s_addc_u32 s34, s0, 0
	v_lshl_add_u64 v[16:17], s[8:9], 0, v[16:17]
	s_mov_b64 s[0:1], 0x3a00000
	v_lshl_add_u64 v[216:217], v[16:17], 0, s[0:1]
	v_readlane_b32 s0, v252, 2
	v_readlane_b32 s1, v252, 3
	s_lshl_b32 s35, s41, 4
	s_nop 0
	v_lshl_add_u64 v[218:219], s[0:1], 0, v[208:209]
	s_branch .LBB0_725

.LBB0_732:
	s_lshl_b64 s[2:3], s[2:3], 12
	s_waitcnt lgkmcnt(0)
	s_add_u32 s0, s0, s2
	v_lshlrev_b32_e32 v144, 2, v235
	s_addc_u32 s1, s1, s3
	v_lshlrev_b32_e32 v208, 2, v144
	global_load_dwordx4 v[204:207], v208, s[0:1]
	global_load_dwordx4 v[188:191], v208, s[0:1] offset:1024
	global_load_dwordx4 v[180:183], v208, s[0:1] offset:2048
	global_load_dwordx4 v[172:175], v208, s[0:1] offset:3072
	v_readlane_b32 s2, v251, 30
	v_readlane_b32 s3, v251, 31
	s_andn2_b64 vcc, exec, s[2:3]
	s_nop 0
	v_cndmask_b32_e64 v144, 0, 1, s[2:3]
	v_cmp_ne_u32_e64 s[0:1], 1, v144
	s_cbranch_vccnz .LBB0_734
	s_add_i32 s3, s10, 0xffffc000
	s_lshr_b32 s3, s3, 2
	s_ashr_i32 s2, s10, 12
	s_add_i32 s3, s3, 4
	s_cmpk_lt_i32 s10, 0x4000
	s_cselect_b32 s2, s2, s3
	s_mul_hi_i32 s3, s2, 0x6000
	s_mulk_i32 s2, 0x6000
	s_add_u32 s2, s31, s2
	s_addc_u32 s3, s34, s3
	v_lshl_add_u64 v[64:65], s[2:3], 0, v[208:209]
	s_mov_b64 s[8:9], 0x1000
	v_add_co_u32_e32 v74, vcc, 0x1000, v64
	v_lshl_add_u64 v[72:73], v[64:65], 0, s[8:9]
	s_nop 0
	v_addc_co_u32_e32 v75, vcc, 0, v65, vcc
	global_load_dwordx4 v[120:123], v208, s[2:3]
	global_load_dwordx4 v[124:127], v208, s[2:3] offset:1024
	global_load_dwordx4 v[68:71], v[72:73], off offset:1024
	global_load_dwordx4 v[64:67], v[72:73], off offset:2048
	global_load_dwordx4 v[80:83], v[74:75], off
	s_nop 0
	global_load_dwordx4 v[72:75], v[72:73], off offset:3072
	s_nop 0
	global_load_dwordx4 v[140:143], v208, s[2:3] offset:2048
	global_load_dwordx4 v[136:139], v208, s[2:3] offset:3072

.LBB0_741:
	s_lshl_b64 s[16:17], s[16:17], 12
	s_waitcnt lgkmcnt(0)
	s_add_u32 s14, s14, s16
	s_addc_u32 s15, s15, s17
	global_load_dwordx4 v[200:203], v208, s[14:15]
	global_load_dwordx4 v[184:187], v208, s[14:15] offset:1024
	global_load_dwordx4 v[176:179], v208, s[14:15] offset:2048
	global_load_dwordx4 v[164:167], v208, s[14:15] offset:3072
	s_and_b64 vcc, exec, s[0:1]
	s_cbranch_vccnz .LBB0_743
	s_add_i32 s11, s12, 0xffffc000
	s_lshr_b32 s11, s11, 2
	s_ashr_i32 s9, s12, 12
	s_add_i32 s11, s11, 4
	s_cmpk_lt_i32 s12, 0x4000
	s_cselect_b32 s9, s9, s11
	s_mul_hi_i32 s11, s9, 0x6000
	s_mulk_i32 s9, 0x6000
	s_add_u32 s12, s31, s9
	s_addc_u32 s13, s34, s11
	v_lshl_add_u64 v[48:49], s[12:13], 0, v[208:209]
	s_mov_b64 s[14:15], 0x1000
	v_add_co_u32_e32 v58, vcc, 0x1000, v48
	v_lshl_add_u64 v[56:57], v[48:49], 0, s[14:15]
	s_nop 0
	v_addc_co_u32_e32 v59, vcc, 0, v49, vcc
	global_load_dwordx4 v[104:107], v208, s[12:13]
	global_load_dwordx4 v[108:111], v208, s[12:13] offset:1024
	global_load_dwordx4 v[52:55], v[56:57], off offset:1024
	global_load_dwordx4 v[48:51], v[56:57], off offset:2048
	global_load_dwordx4 v[60:63], v[58:59], off
	s_nop 0
	global_load_dwordx4 v[56:59], v[56:57], off offset:3072
	s_nop 0
	global_load_dwordx4 v[132:135], v208, s[12:13] offset:2048
	global_load_dwordx4 v[128:131], v208, s[12:13] offset:3072

.LBB0_750:
	s_lshl_b64 s[22:23], s[22:23], 12
	s_waitcnt lgkmcnt(0)
	s_add_u32 s16, s16, s22
	s_addc_u32 s17, s17, s23
	global_load_dwordx4 v[196:199], v208, s[16:17]
	global_load_dwordx4 v[168:171], v208, s[16:17] offset:1024
	global_load_dwordx4 v[160:163], v208, s[16:17] offset:2048
	global_load_dwordx4 v[152:155], v208, s[16:17] offset:3072
	s_and_b64 vcc, exec, s[0:1]
	s_cbranch_vccnz .LBB0_752
	s_add_i32 s11, s12, 0xffffc000
	s_lshr_b32 s11, s11, 2
	s_ashr_i32 s9, s12, 12
	s_add_i32 s11, s11, 4
	s_cmpk_lt_i32 s12, 0x4000
	s_cselect_b32 s9, s9, s11
	s_mul_hi_i32 s11, s9, 0x6000
	s_mulk_i32 s9, 0x6000
	s_add_u32 s12, s31, s9
	s_addc_u32 s13, s34, s11
	v_lshl_add_u64 v[32:33], s[12:13], 0, v[208:209]
	s_mov_b64 s[16:17], 0x1000
	v_add_co_u32_e32 v42, vcc, 0x1000, v32
	v_lshl_add_u64 v[40:41], v[32:33], 0, s[16:17]
	s_nop 0
	v_addc_co_u32_e32 v43, vcc, 0, v33, vcc
	global_load_dwordx4 v[88:91], v208, s[12:13]
	global_load_dwordx4 v[92:95], v208, s[12:13] offset:1024
	global_load_dwordx4 v[36:39], v[40:41], off offset:1024
	global_load_dwordx4 v[32:35], v[40:41], off offset:2048
	global_load_dwordx4 v[44:47], v[42:43], off
	s_nop 0
	global_load_dwordx4 v[40:43], v[40:41], off offset:3072
	s_nop 0
	global_load_dwordx4 v[116:119], v208, s[12:13] offset:2048
	global_load_dwordx4 v[112:115], v208, s[12:13] offset:3072
